# loop-edge edit 2: step-A barrier edge - V-slot ring update in front of the barrier, rescale block out of line
# speedup vs baseline: 1.0220x; 1.0007x over previous
.LBB0_833:
	s_waitcnt lgkmcnt(6)
	v_mfma_f32_32x32x16_bf16 v[48:63], v[180:183], v[6:9], v[48:63]
	v_exp_f32_e32 v128, v128
	v_exp_f32_e32 v129, v129
	v_exp_f32_e32 v130, v130
	v_exp_f32_e32 v131, v131
	ds_read_b64_tr_b16 v[6:7], v14 offset:51200
	ds_read_b64_tr_b16 v[8:9], v14 offset:51712
	s_waitcnt lgkmcnt(6)
	v_mfma_f32_32x32x16_bf16 v[32:47], v[180:183], v[10:13], v[32:47]
	v_exp_f32_e32 v132, v132
	v_exp_f32_e32 v133, v133
	v_exp_f32_e32 v134, v134
	v_exp_f32_e32 v135, v135
	ds_read_b64_tr_b16 v[10:11], v14 offset:55296
	ds_read_b64_tr_b16 v[12:13], v14 offset:55808
	s_waitcnt lgkmcnt(6)
	v_mfma_f32_32x32x16_bf16 v[48:63], v[172:175], v[80:83], v[48:63]
	v_exp_f32_e32 v136, v136
	v_exp_f32_e32 v137, v137
	v_exp_f32_e32 v138, v138
	v_exp_f32_e32 v139, v139
	ds_read_b64_tr_b16 v[80:81], v14 offset:52224
	ds_read_b64_tr_b16 v[82:83], v14 offset:52736
	s_waitcnt lgkmcnt(6)
	v_mfma_f32_32x32x16_bf16 v[32:47], v[172:175], v[2:5], v[32:47]
	v_exp_f32_e32 v140, v140
	v_exp_f32_e32 v141, v141
	v_exp_f32_e32 v142, v142
	v_exp_f32_e32 v143, v143
	v_add_u32_e32 v15, s12, v214
	ds_read_b64_tr_b16 v[84:85], v14 offset:56320
	ds_read_b64_tr_b16 v[86:87], v14 offset:56832
	ds_read_b128 v[2:5], v15
	s_waitcnt lgkmcnt(7)
	v_mfma_f32_32x32x16_bf16 v[48:63], v[160:163], v[6:9], v[48:63]
	v_exp_f32_e32 v112, v112
	v_exp_f32_e32 v113, v113
	v_exp_f32_e32 v114, v114
	v_exp_f32_e32 v115, v115
	ds_read_b128 v[6:9], v15 offset:512
	s_waitcnt lgkmcnt(6)
	v_mfma_f32_32x32x16_bf16 v[32:47], v[160:163], v[10:13], v[32:47]
	v_exp_f32_e32 v116, v116
	v_exp_f32_e32 v117, v117
	v_exp_f32_e32 v118, v118
	v_exp_f32_e32 v119, v119
	ds_read_b128 v[10:13], v15 offset:2048
	s_waitcnt lgkmcnt(5)
	v_mfma_f32_32x32x16_bf16 v[48:63], v[152:155], v[80:83], v[48:63]
	v_exp_f32_e32 v120, v120
	v_exp_f32_e32 v121, v121
	v_exp_f32_e32 v122, v122
	v_exp_f32_e32 v123, v123
	ds_read_b128 v[184:187], v15 offset:2560
	s_waitcnt lgkmcnt(4)
	v_mfma_f32_32x32x16_bf16 v[32:47], v[152:155], v[84:87], v[32:47]
	v_exp_f32_e32 v124, v124
	v_exp_f32_e32 v125, v125
	v_exp_f32_e32 v126, v126
	v_exp_f32_e32 v127, v127
	s_add_i32 s12, s23, 0x2000
	s_cmpk_lg_i32 s23, 0x4000
	s_cselect_b32 s12, s12, 0
	s_waitcnt vmcnt(3) lgkmcnt(0)
	s_barrier
	s_andn2_b64 vcc, exec, s[62:63]
	s_cbranch_vccz .Latt_rA
.LBB0_835:
	ds_read_b128 v[188:191], v15 offset:4096
	v_add_u32_e32 v14, s10, v217
	s_waitcnt lgkmcnt(4)
	v_mfma_f32_32x32x16_bf16 v[96:111], v[2:5], v[176:179], v[64:79]
	v_add_f32_e32 v80, v128, v129
	v_add_f32_e32 v80, v130, v80
	v_add_f32_e32 v80, v131, v80
	v_add_f32_e32 v80, v132, v80
	v_cvt_pk_bf16_f32 v180, v128, v129
	ds_read_b128 v[2:5], v15 offset:4608
	v_add_f32_e32 v80, v133, v80
	v_add_f32_e32 v80, v134, v80
	v_add_f32_e32 v128, v135, v80
	s_waitcnt lgkmcnt(4)
	v_mfma_f32_32x32x16_bf16 v[80:95], v[6:9], v[176:179], v[64:79]
	v_cvt_pk_bf16_f32 v181, v130, v131
	s_add_i32 s10, s22, s78
	s_mov_b32 m0, s10
	s_nop 0
	global_load_lds_dwordx4 v216, s[58:59]
	ds_read_b128 v[6:9], v15 offset:6144
	s_waitcnt lgkmcnt(4)
	v_mfma_f32_32x32x16_bf16 v[96:111], v[10:13], v[168:171], v[96:111]
	v_add_f32_e32 v128, v136, v128
	v_add_f32_e32 v128, v137, v128
	v_add_f32_e32 v128, v138, v128
	v_cvt_pk_bf16_f32 v182, v132, v133
	ds_read_b128 v[10:13], v15 offset:6656
	s_waitcnt lgkmcnt(4)
	v_mfma_f32_32x32x16_bf16 v[80:95], v[184:187], v[168:171], v[80:95]
	v_add_f32_e32 v128, v139, v128
	v_add_f32_e32 v128, v140, v128
	v_add_f32_e32 v132, v141, v128
	v_cvt_pk_bf16_f32 v183, v134, v135
	s_add_i32 s10, s22, s85
	s_mov_b32 m0, s10
	s_nop 0
	global_load_lds_dwordx4 v216, s[60:61]
	ds_read_b128 v[128:131], v15 offset:8192
	s_waitcnt lgkmcnt(4)
	v_mfma_f32_32x32x16_bf16 v[96:111], v[188:191], v[164:167], v[96:111]
	v_add_f32_e32 v132, v142, v132
	v_add_f32_e32 v132, v143, v132
	v_add_f32_e32 v152, v112, v132
	v_cvt_pk_bf16_f32 v172, v136, v137
	ds_read_b128 v[132:135], v15 offset:8704
	s_waitcnt lgkmcnt(4)
	v_mfma_f32_32x32x16_bf16 v[80:95], v[2:5], v[164:167], v[80:95]
	v_add_f32_e32 v136, v113, v152
	v_add_f32_e32 v136, v114, v136
	v_add_f32_e32 v136, v115, v136
	v_cvt_pk_bf16_f32 v173, v138, v139
	s_add_i32 s10, s12, s86
	s_mov_b32 m0, s10
	s_nop 0
	global_load_lds_dwordx4 v216, s[6:7]
	ds_read_b128 v[2:5], v15 offset:10240
	s_waitcnt lgkmcnt(4)
	v_mfma_f32_32x32x16_bf16 v[96:111], v[6:9], v[156:159], v[96:111]
	v_add_f32_e32 v136, v116, v136
	v_add_f32_e32 v152, v117, v136
	v_cvt_pk_bf16_f32 v174, v140, v141
	v_cvt_pk_bf16_f32 v175, v142, v143
	ds_read_b128 v[136:139], v15 offset:10752
	s_waitcnt lgkmcnt(4)
	v_mfma_f32_32x32x16_bf16 v[80:95], v[10:13], v[156:159], v[80:95]
	v_add_f32_e32 v6, v118, v152
	v_add_f32_e32 v6, v119, v6
	v_cvt_pk_bf16_f32 v160, v112, v113
	v_cvt_pk_bf16_f32 v161, v114, v115
	ds_read_b64_tr_b16 v[112:113], v14 offset:49152
	ds_read_b64_tr_b16 v[114:115], v14 offset:49664
	s_waitcnt lgkmcnt(5)
	v_mfma_f32_32x32x16_bf16 v[96:111], v[128:131], v[148:151], v[96:111]
	v_add_f32_e32 v6, v120, v6
	v_add_f32_e32 v6, v121, v6
	v_cvt_pk_bf16_f32 v162, v116, v117
	v_cvt_pk_bf16_f32 v163, v118, v119
	ds_read_b64_tr_b16 v[10:11], v14 offset:53248
	ds_read_b64_tr_b16 v[12:13], v14 offset:53760
	s_waitcnt lgkmcnt(6)
	v_mfma_f32_32x32x16_bf16 v[80:95], v[132:135], v[148:151], v[80:95]
	v_add_f32_e32 v6, v122, v6
	v_add_f32_e32 v15, v123, v6
	v_cvt_pk_bf16_f32 v152, v120, v121
	v_cvt_pk_bf16_f32 v153, v122, v123
	ds_read_b64_tr_b16 v[6:7], v14 offset:50176
	ds_read_b64_tr_b16 v[8:9], v14 offset:50688
	s_waitcnt lgkmcnt(7)
	v_mfma_f32_32x32x16_bf16 v[96:111], v[2:5], v[144:147], v[96:111]
	v_add_f32_e32 v15, v124, v15
	v_add_f32_e32 v15, v125, v15
	v_cvt_pk_bf16_f32 v154, v124, v125
	ds_read_b64_tr_b16 v[2:3], v14 offset:54272
	ds_read_b64_tr_b16 v[4:5], v14 offset:54784
	s_waitcnt lgkmcnt(8)
	v_mfma_f32_32x32x16_bf16 v[80:95], v[136:139], v[144:147], v[80:95]
	v_add_f32_e32 v15, v126, v15
	v_add_f32_e32 v15, v127, v15
	v_cvt_pk_bf16_f32 v155, v126, v127
	s_nop 1
	v_max_f32_e32 v116, v96, v97
	s_add_i32 s10, s67, -1
	s_and_b32 s22, s10, 3
	s_mulk_i32 s22, 0x3000
	s_nop 2
	v_max3_f32 v117, v98, v99, v81
	v_max3_f32 v116, v116, v80, v82
	v_max3_f32 v116, v116, v83, v100
	v_max3_f32 v117, v117, v102, v103
	v_max3_f32 v116, v116, v101, v84
	v_max3_f32 v117, v117, v86, v87
	v_max3_f32 v116, v116, v85, v104
	v_max3_f32 v117, v117, v106, v107
	v_max3_f32 v116, v116, v105, v88
	v_max3_f32 v117, v117, v90, v91
	v_max3_f32 v116, v116, v89, v108
	v_max3_f32 v117, v117, v110, v111
	v_max3_f32 v116, v116, v109, v92
	v_max3_f32 v117, v117, v94, v95
	v_add_f32_e32 v218, v0, v15
	v_max3_f32 v0, v116, v93, v117
	v_mov_b32_e32 v15, v0
	s_nop 1
	v_permlane32_swap_b32_e32 v0, v15
	v_max_f32_e32 v0, v0, v15
	v_cmp_lt_f32_e32 vcc, s94, v0
	s_cmp_lg_u64 vcc, 0
	s_cselect_b64 s[62:63], -1, 0
	s_cbranch_vccnz .LBB0_843

.Latt_rA:
	s_waitcnt lgkmcnt(0)
	ds_read_b128 v[80:83], v207 offset:96
	ds_read_b128 v[84:87], v207 offset:64
	ds_read_b128 v[88:91], v207 offset:32
	ds_read_b128 v[92:95], v207
	s_waitcnt lgkmcnt(3)
	v_pk_mul_f32 v[62:63], v[62:63], v[82:83]
	s_waitcnt lgkmcnt(2)
	v_pk_mul_f32 v[58:59], v[58:59], v[86:87]
	s_waitcnt lgkmcnt(1)
	v_pk_mul_f32 v[54:55], v[54:55], v[90:91]
	s_waitcnt lgkmcnt(0)
	v_pk_mul_f32 v[50:51], v[50:51], v[94:95]
	v_pk_mul_f32 v[60:61], v[60:61], v[80:81]
	v_pk_mul_f32 v[56:57], v[56:57], v[84:85]
	v_pk_mul_f32 v[52:53], v[52:53], v[88:89]
	v_pk_mul_f32 v[48:49], v[48:49], v[92:93]
	v_pk_mul_f32 v[46:47], v[46:47], v[82:83]
	v_pk_mul_f32 v[42:43], v[42:43], v[86:87]
	v_pk_mul_f32 v[38:39], v[38:39], v[90:91]
	v_pk_mul_f32 v[34:35], v[34:35], v[94:95]
	v_pk_mul_f32 v[44:45], v[44:45], v[80:81]
	v_pk_mul_f32 v[40:41], v[40:41], v[84:85]
	v_pk_mul_f32 v[36:37], v[36:37], v[88:89]
	v_pk_mul_f32 v[32:33], v[32:33], v[92:93]
	s_branch .LBB0_835
